# v054 plus K-fragment LDS reads hoisted above the bias init in the slc, window (unmasked), cmp1 (path B) and cmp2 tiles
# baseline (speedup 1.0000x reference)
; template <int MODE>
; DI void bias_init(f32x16& s0, f32x16& s1, const TP& tp, float fbm, int hi) {
; #pragma unroll
;     for (int r = 0; r < 16; ++r) {
;         const int kvc = 16 * (r >> 3) + (r & 7);
;         if (MODE == 0) { s0[r] = __builtin_fmaf(-L2E, tp.cs[kvc + 8 * hi], fbm); s1[r] = __builtin_fmaf(-L2E, tp.cs[kvc + 32 + 8 * hi], fbm); }
;         else { s0[r] = __builtin_fmaf(tp.sl, (float)kvc, fbm); s1[r] = __builtin_fmaf(tp.sl, (float)(kvc + 32), fbm); }
;     }
; }
; DI float max3_asm(float a, float b, float c) { float r; asm("v_max3_f32 %0, %1, %2, %3" : "=v"(r) : "v"(a), "v"(b), "v"(c)); return r; }
; template <bool MASK>
; DI float mask_rowmax(f32x16& s0, f32x16& s1, const TP& tp) {
;     if (MASK) {
; #pragma unroll
;         for (int r = 0; r < 16; ++r) {
;             const int kvc = 16 * (r >> 3) + (r & 7);
;             const bool v0 = tp.sel && (kvc <= tp.lim) && (kvc > tp.lim2), v1 = tp.sel && (kvc + 32 <= tp.lim) && (kvc + 32 > tp.lim2);
;             s0[r] = v0 ? s0[r] : -1e30f; s1[r] = v1 ? s1[r] : -1e30f;
;         }
;     }
;     const float seed = __builtin_fminf(s0[15], s1[15]);
;     float ma = seed, mb = seed;
; #pragma unroll
;     for (int r = 0; r < 16; r += 2) { ma = max3_asm(ma, s0[r], s1[r]); mb = max3_asm(mb, s0[r + 1], s1[r + 1]); }
;     const float mx = fmaxf(ma, mb);
;     return fmaxf(mx, __shfl_xor(mx, 32));
; }
; template <int MODE, bool MASK, bool WITH_O>
; DI void attn_tile_t(lptr Kt, lptr Vt, const bf16x8 (&qf)[4], f32x16& o0, f32x16& o1, RowState& rs, const TP& tp, int lane) {
;     const int hi = lane >> 5;
;     f32x16 s0, s1;
;     bias_init<MODE>(s0, s1, tp, tp.fb - rs.mref, hi);
;     qk_acc(Kt, qf, s0, s1, lane);
;     const float mx = mask_rowmax<MASK>(s0, s1, tp);
;     const bool was = rs.seen; rs.seen = was || (mx > -1e29f);
;     const bool trig = (mx > 8.f) || (!was && mx > -1e29f && mx < -8.f);
;     if (__builtin_expect(__any(trig), 0)) {
.LBB0_535:
	s_and_b64 vcc, exec, s[2:3]
	s_cbranch_vccz .LBB0_531
	v_sub_f32_e32 v18, v50, v49
	v_add3_u32 v232, s52, v131, v133
	ds_read_b128 v[50:53], v232 offset:4608
	ds_read_b128 v[54:57], v232
	ds_read_b128 v[58:61], v232 offset:32
	ds_read_b128 v[62:65], v232 offset:4640
	ds_read_b128 v[66:69], v232 offset:64
	ds_read_b128 v[70:73], v232 offset:4672
	ds_read_b128 v[88:91], v232 offset:96
	ds_read_b128 v[92:95], v232 offset:4704
	s_mov_b32 s2, 2.0
	v_mov_b32_e32 v79, v78
	s_mov_b32 s3, 0x40400000
	v_pk_fma_f32 v[32:33], v[78:79], s[4:5], v[18:19] op_sel_hi:[1,1,0]
	v_pk_fma_f32 v[30:31], v[78:79], s[14:15], v[18:19] op_sel_hi:[1,1,0]
	v_pk_fma_f32 v[28:29], v[78:79], s[16:17], v[18:19] op_sel_hi:[1,1,0]
	v_pk_fma_f32 v[26:27], v[78:79], s[94:95], v[18:19] op_sel_hi:[1,1,0]
	v_pk_fma_f32 v[24:25], v[78:79], s[96:97], v[18:19] op_sel_hi:[1,1,0]
	v_pk_fma_f32 v[22:23], v[78:79], s[84:85], v[18:19] op_sel_hi:[1,1,0]
	v_pk_fma_f32 v[20:21], v[78:79], s[72:73], v[18:19] op_sel_hi:[1,1,0]
	v_pk_fma_f32 v[4:5], v[80:81], s[2:3], v[18:19] op_sel_hi:[1,1,0]
	s_mov_b32 s2, 4.0
	s_mov_b32 s3, 0x40a00000
	v_pk_fma_f32 v[6:7], v[80:81], s[2:3], v[18:19] op_sel_hi:[1,1,0]
	s_mov_b32 s2, 0x40c00000
	s_mov_b32 s3, 0x40e00000
	v_pk_fma_f32 v[8:9], v[80:81], s[2:3], v[18:19] op_sel_hi:[1,1,0]
	s_mov_b32 s2, 0x41800000
	s_mov_b32 s3, 0x41880000
	v_pk_fma_f32 v[10:11], v[80:81], s[2:3], v[18:19] op_sel_hi:[1,1,0]
	s_mov_b32 s2, 0x41900000
	s_mov_b32 s3, 0x41980000
	v_pk_fma_f32 v[12:13], v[80:81], s[2:3], v[18:19] op_sel_hi:[1,1,0]
	s_mov_b32 s2, 0x41a00000
	s_mov_b32 s3, 0x41a80000
	v_fma_f32 v2, 0, v78, v18
	v_add_f32_e32 v3, v78, v18
	v_pk_fma_f32 v[14:15], v[80:81], s[2:3], v[18:19] op_sel_hi:[1,1,0]
	v_pk_fma_f32 v[16:17], v[80:81], s[18:19], v[18:19] op_sel_hi:[1,1,0]
	v_pk_fma_f32 v[18:19], v[82:83], s[44:45], v[18:19] op_sel_hi:[1,1,0]
	s_setprio 1
	s_waitcnt vmcnt(4) lgkmcnt(6)
	v_mfma_f32_32x32x16_bf16 v[2:17], v[54:57], v[98:101], v[2:17]
	v_mfma_f32_32x32x16_bf16 v[18:33], v[50:53], v[98:101], v[18:33]
	s_waitcnt vmcnt(3) lgkmcnt(5)
	v_mfma_f32_32x32x16_bf16 v[2:17], v[58:61], v[102:105], v[2:17]
	s_waitcnt lgkmcnt(4)
	v_mfma_f32_32x32x16_bf16 v[18:33], v[62:65], v[102:105], v[18:33]
	s_waitcnt vmcnt(2) lgkmcnt(3)
	v_mfma_f32_32x32x16_bf16 v[2:17], v[66:69], v[106:109], v[2:17]
	s_waitcnt lgkmcnt(2)
	v_mfma_f32_32x32x16_bf16 v[18:33], v[70:73], v[106:109], v[18:33]
	s_waitcnt vmcnt(1) lgkmcnt(1)
	v_mfma_f32_32x32x16_bf16 v[2:17], v[88:91], v[110:113], v[2:17]
	s_waitcnt lgkmcnt(0)
	v_mfma_f32_32x32x16_bf16 v[18:33], v[92:95], v[110:113], v[18:33]
	s_setprio 0
	v_cmp_lt_i32_e32 vcc, 0, v48
	s_mov_b32 s2, 0xefa18f08
	s_nop 6
	v_cndmask_b32_e32 v51, v210, v3, vcc
	v_cmp_lt_i32_e32 vcc, -1, v48
	s_nop 1
	v_cndmask_b32_e32 v55, v210, v2, vcc
	v_cmp_lt_i32_e32 vcc, 32, v48
	s_nop 1
	v_cndmask_b32_e32 v53, v210, v19, vcc
	v_cmp_lt_i32_e32 vcc, 31, v48
	s_nop 1
	v_cndmask_b32_e32 v58, v210, v18, vcc
	v_cmp_lt_i32_e32 vcc, 2, v48
	s_nop 1
	v_cndmask_b32_e32 v50, v210, v5, vcc
	v_cmp_lt_i32_e32 vcc, 1, v48
	s_nop 1
	v_cndmask_b32_e32 v57, v210, v4, vcc
	v_cmp_lt_i32_e32 vcc, 34, v48
	s_nop 1
	v_cndmask_b32_e32 v21, v210, v21, vcc
	v_cmp_lt_i32_e32 vcc, 33, v48
	s_nop 1
	v_cndmask_b32_e32 v59, v210, v20, vcc
	v_cmp_lt_i32_e32 vcc, 4, v48
	s_nop 1
	v_cndmask_b32_e32 v18, v210, v7, vcc
	v_cmp_lt_i32_e32 vcc, 3, v48
	s_nop 1
	v_cndmask_b32_e32 v54, v210, v6, vcc
	v_cmp_lt_i32_e32 vcc, 36, v48
	s_nop 1
	v_cndmask_b32_e32 v20, v210, v23, vcc
	v_cmp_lt_i32_e32 vcc, 35, v48
	s_nop 1
	v_cndmask_b32_e32 v56, v210, v22, vcc
	v_cmp_lt_i32_e32 vcc, 6, v48
	s_nop 1
	v_cndmask_b32_e32 v9, v210, v9, vcc
	v_cmp_lt_i32_e32 vcc, 5, v48
	s_nop 1
	v_cndmask_b32_e32 v52, v210, v8, vcc
	v_cmp_lt_i32_e32 vcc, 38, v48
	s_nop 1
	v_cndmask_b32_e32 v19, v210, v25, vcc
	v_cmp_lt_i32_e32 vcc, 37, v48
	s_nop 1
	v_cndmask_b32_e32 v25, v210, v24, vcc
	v_cmp_lt_i32_e32 vcc, 16, v48
	s_nop 1
	v_cndmask_b32_e32 v6, v210, v11, vcc
	v_cmp_lt_i32_e32 vcc, 15, v48
	s_nop 1
	v_cndmask_b32_e32 v22, v210, v10, vcc
	v_cmp_lt_i32_e32 vcc, 48, v48
	s_nop 1
	v_cndmask_b32_e32 v8, v210, v27, vcc
	v_cmp_lt_i32_e32 vcc, 47, v48
	s_nop 1
	v_cndmask_b32_e32 v24, v210, v26, vcc
	v_cmp_lt_i32_e32 vcc, 18, v48
	v_and_b32_e32 v26, 64, v209
	v_add_u32_e32 v26, 64, v26
	v_cndmask_b32_e32 v4, v210, v13, vcc
	v_cmp_lt_i32_e32 vcc, 17, v48
	s_nop 1
	v_cndmask_b32_e32 v13, v210, v12, vcc
	v_cmp_lt_i32_e32 vcc, 50, v48
	s_nop 1
	v_cndmask_b32_e32 v7, v210, v29, vcc
	v_cmp_lt_i32_e32 vcc, 49, v48
	s_nop 1
	v_cndmask_b32_e32 v23, v210, v28, vcc
	v_cmp_lt_i32_e32 vcc, 20, v48
	s_nop 1
	v_cndmask_b32_e32 v3, v210, v15, vcc
	v_cmp_lt_i32_e32 vcc, 19, v48
	s_nop 1
	v_cndmask_b32_e32 v11, v210, v14, vcc
	v_cmp_lt_i32_e32 vcc, 52, v48
	s_nop 1
	v_cndmask_b32_e32 v5, v210, v31, vcc
	v_cmp_lt_i32_e32 vcc, 51, v48
	s_nop 1
	v_cndmask_b32_e32 v14, v210, v30, vcc
	v_cmp_lt_i32_e32 vcc, 22, v48
	s_nop 1
	v_cndmask_b32_e32 v2, v210, v17, vcc
	v_cmp_lt_i32_e32 vcc, 21, v48
	s_nop 1
	v_cndmask_b32_e32 v10, v210, v16, vcc
	v_cmp_lt_i32_e32 vcc, 54, v48
	v_max_f32_e32 v16, v2, v2
	s_nop 0
	v_cndmask_b32_e32 v17, v210, v33, vcc
	v_max_f32_e32 v15, v17, v17
	v_min_f32_e32 v15, v16, v15
	v_max3_f32 v16, v15, v55, v58
	v_max3_f32 v15, v15, v51, v53
	v_cmp_lt_i32_e32 vcc, 53, v48
	v_max3_f32 v16, v16, v57, v59
	v_max3_f32 v15, v15, v50, v21
	s_nop 0
	v_max3_f32 v16, v16, v54, v56
	v_max3_f32 v15, v15, v18, v20
	s_nop 0
	v_cndmask_b32_e32 v12, v210, v32, vcc
	v_max3_f32 v16, v16, v52, v25
	v_max3_f32 v15, v15, v9, v19
	s_nop 0
	v_max3_f32 v16, v16, v22, v24
	v_max3_f32 v15, v15, v6, v8
	s_nop 0
	v_max3_f32 v16, v16, v13, v23
	v_max3_f32 v15, v15, v4, v7
	s_nop 0
	v_max3_f32 v16, v16, v11, v14
	v_max3_f32 v15, v15, v3, v5
	s_nop 0
	v_max3_f32 v16, v16, v10, v12
	v_max3_f32 v15, v15, v2, v17
	s_nop 0
	v_max_f32_e32 v15, v15, v15
	v_max_f32_e32 v16, v16, v16
	v_max_f32_e32 v15, v16, v15
	v_mov_b32_e32 v16, v15
	s_nop 1
	v_permlane32_swap_b32_e32 v16, v15
	s_waitcnt lgkmcnt(0)
	v_max_f32_e32 v15, v15, v16
	v_cmp_lt_f32_e64 s[24:25], s2, v15
	s_mov_b32 s2, 0x41000000
	v_cmp_lt_f32_e32 vcc, s2, v15
	s_mov_b32 s2, 0xc1000000
	v_cmp_gt_f32_e64 s[2:3], s2, v15
	s_and_b64 s[2:3], s[2:3], s[24:25]
	s_andn2_b64 s[2:3], s[2:3], s[0:1]
	s_or_b64 s[2:3], s[2:3], vcc
	s_and_b64 vcc, exec, s[2:3]
	s_cbranch_vccnz .LBB0_541

; template <int MODE>
; DI void bias_init(f32x16& s0, f32x16& s1, const TP& tp, float fbm, int hi) {
; #pragma unroll
;     for (int r = 0; r < 16; ++r) {
;         const int kvc = 16 * (r >> 3) + (r & 7);
;         if (MODE == 0) { s0[r] = __builtin_fmaf(-L2E, tp.cs[kvc + 8 * hi], fbm); s1[r] = __builtin_fmaf(-L2E, tp.cs[kvc + 32 + 8 * hi], fbm); }
;         else { s0[r] = __builtin_fmaf(tp.sl, (float)kvc, fbm); s1[r] = __builtin_fmaf(tp.sl, (float)(kvc + 32), fbm); }
;     }
; }
; DI float max3_asm(float a, float b, float c) { float r; asm("v_max3_f32 %0, %1, %2, %3" : "=v"(r) : "v"(a), "v"(b), "v"(c)); return r; }
; template <bool MASK>
; DI float mask_rowmax(f32x16& s0, f32x16& s1, const TP& tp) {
;     if (MASK) {
; #pragma unroll
;         for (int r = 0; r < 16; ++r) {
;             const int kvc = 16 * (r >> 3) + (r & 7);
;             const bool v0 = tp.sel && (kvc <= tp.lim) && (kvc > tp.lim2), v1 = tp.sel && (kvc + 32 <= tp.lim) && (kvc + 32 > tp.lim2);
;             s0[r] = v0 ? s0[r] : -1e30f; s1[r] = v1 ? s1[r] : -1e30f;
; DI void cmpwin_unit(const Params& P, lptr L, int u, int tid, int lane, int wid) {
;     ...
;             const int n0 = jt * 64;
;             TP tp; tp.cs = nullptr; tp.sl = 16.f * sl; tp.fb = sl * (float)(16 * (n0 + 8 * hi) + 31 - t); tp.lim = nlim - n0 - 8 * hi; tp.lim2 = -(1 << 30); tp.sel = true;
;             f32x16 s0, s1;
;             bias_init<1>(s0, s1, tp, tp.fb - mfin, hi);
;             qk_acc(Kt, qf, s0, s1, lane);
;             if (n0 + 63 > nfull) (void)mask_rowmax<true>(s0, s1, tp);
.LBB0_548:
	s_and_b32 s25, s24, 1
	s_mul_i32 s26, s25, 0x2400
	v_add_u32_e32 v232, s26, v170
	ds_read_b128 v[90:93], v232 offset:4608
	ds_read_b128 v[94:97], v232
	ds_read_b128 v[114:117], v232 offset:32
	ds_read_b128 v[118:121], v232 offset:4640
	ds_read_b128 v[154:157], v232 offset:64
	ds_read_b128 v[158:161], v232 offset:4672
	ds_read_b128 v[162:165], v232 offset:96
	ds_read_b128 v[166:169], v232 offset:4704
	s_lshl_b32 s2, s24, 6
	v_or_b32_e32 v88, s2, v126
	v_lshlrev_b32_e32 v34, 4, v88
	v_sub_u32_e32 v34, v34, v85
	v_add_u32_e32 v34, 31, v34
	v_cvt_f32_i32_e32 v34, v34
	s_mov_b32 s22, 2.0
	v_fma_f32 v50, v150, v34, -v87
	v_mov_b32_e32 v79, v78
	s_mov_b32 s23, 0x40400000
	v_pk_fma_f32 v[64:65], v[78:79], s[4:5], v[50:51] op_sel_hi:[1,1,0]
	v_pk_fma_f32 v[62:63], v[78:79], s[14:15], v[50:51] op_sel_hi:[1,1,0]
	v_pk_fma_f32 v[60:61], v[78:79], s[16:17], v[50:51] op_sel_hi:[1,1,0]
	v_pk_fma_f32 v[58:59], v[78:79], s[94:95], v[50:51] op_sel_hi:[1,1,0]
	v_pk_fma_f32 v[56:57], v[78:79], s[96:97], v[50:51] op_sel_hi:[1,1,0]
	v_pk_fma_f32 v[54:55], v[78:79], s[84:85], v[50:51] op_sel_hi:[1,1,0]
	v_pk_fma_f32 v[52:53], v[78:79], s[72:73], v[50:51] op_sel_hi:[1,1,0]
	v_pk_fma_f32 v[36:37], v[80:81], s[22:23], v[50:51] op_sel_hi:[1,1,0]
	s_mov_b32 s22, 4.0
	s_mov_b32 s23, 0x40a00000
	v_pk_fma_f32 v[38:39], v[80:81], s[22:23], v[50:51] op_sel_hi:[1,1,0]
	s_mov_b32 s22, 0x40c00000
	s_mov_b32 s23, 0x40e00000
	v_pk_fma_f32 v[40:41], v[80:81], s[22:23], v[50:51] op_sel_hi:[1,1,0]
	s_mov_b32 s22, 0x41800000
	s_mov_b32 s23, 0x41880000
	v_pk_fma_f32 v[42:43], v[80:81], s[22:23], v[50:51] op_sel_hi:[1,1,0]
	s_mov_b32 s22, 0x41900000
	s_mov_b32 s23, 0x41980000
	v_pk_fma_f32 v[44:45], v[80:81], s[22:23], v[50:51] op_sel_hi:[1,1,0]
	s_mov_b32 s22, 0x41a00000
	s_mov_b32 s23, 0x41a80000
	v_fma_f32 v34, 0, v78, v50
	v_add_f32_e32 v35, v78, v50
	v_pk_fma_f32 v[46:47], v[80:81], s[22:23], v[50:51] op_sel_hi:[1,1,0]
	v_pk_fma_f32 v[48:49], v[80:81], s[18:19], v[50:51] op_sel_hi:[1,1,0]
	v_pk_fma_f32 v[50:51], v[82:83], s[44:45], v[50:51] op_sel_hi:[1,1,0]
	s_setprio 1
	s_waitcnt lgkmcnt(6)
	v_mfma_f32_32x32x16_bf16 v[34:49], v[94:97], v[98:101], v[34:49]
	v_mfma_f32_32x32x16_bf16 v[50:65], v[90:93], v[98:101], v[50:65]
	s_waitcnt lgkmcnt(5)
	v_mfma_f32_32x32x16_bf16 v[34:49], v[114:117], v[102:105], v[34:49]
	s_waitcnt lgkmcnt(4)
	v_mfma_f32_32x32x16_bf16 v[50:65], v[118:121], v[102:105], v[50:65]
	s_waitcnt lgkmcnt(3)
	v_mfma_f32_32x32x16_bf16 v[34:49], v[154:157], v[106:109], v[34:49]
	s_waitcnt lgkmcnt(2)
	v_mfma_f32_32x32x16_bf16 v[50:65], v[158:161], v[106:109], v[50:65]
	s_waitcnt lgkmcnt(1)
	v_mfma_f32_32x32x16_bf16 v[34:49], v[162:165], v[110:113], v[34:49]
	s_waitcnt lgkmcnt(0)
	v_mfma_f32_32x32x16_bf16 v[50:65], v[166:169], v[110:113], v[50:65]
	s_setprio 0
	s_or_b32 s3, s2, 63
	s_cmp_le_i32 s3, s29
	s_cbranch_scc1 .LBB0_550
	v_sub_u32_e32 v79, v86, v88
	v_cmp_lt_i32_e32 vcc, -1, v79
	s_nop 3
	v_cndmask_b32_e32 v34, v210, v34, vcc
	v_cmp_lt_i32_e32 vcc, 31, v79
	s_nop 1
	v_cndmask_b32_e32 v50, v210, v50, vcc
	v_cmp_lt_i32_e32 vcc, 0, v79
	s_nop 1
	v_cndmask_b32_e32 v35, v210, v35, vcc
	v_cmp_lt_i32_e32 vcc, 32, v79
	s_nop 1
	v_cndmask_b32_e32 v51, v210, v51, vcc
	v_cmp_lt_i32_e32 vcc, 1, v79
	s_nop 1
	v_cndmask_b32_e32 v36, v210, v36, vcc
	v_cmp_lt_i32_e32 vcc, 33, v79
	s_nop 1
	v_cndmask_b32_e32 v52, v210, v52, vcc
	v_cmp_lt_i32_e32 vcc, 2, v79
	s_nop 1
	v_cndmask_b32_e32 v37, v210, v37, vcc
	v_cmp_lt_i32_e32 vcc, 34, v79
	s_nop 1
	v_cndmask_b32_e32 v53, v210, v53, vcc
	v_cmp_lt_i32_e32 vcc, 3, v79
	s_nop 1
	v_cndmask_b32_e32 v38, v210, v38, vcc
	v_cmp_lt_i32_e32 vcc, 35, v79
	s_nop 1
	v_cndmask_b32_e32 v54, v210, v54, vcc
	v_cmp_lt_i32_e32 vcc, 4, v79
	s_nop 1
	v_cndmask_b32_e32 v39, v210, v39, vcc
	v_cmp_lt_i32_e32 vcc, 36, v79
	s_nop 1
	v_cndmask_b32_e32 v55, v210, v55, vcc
	v_cmp_lt_i32_e32 vcc, 5, v79
	s_nop 1
	v_cndmask_b32_e32 v40, v210, v40, vcc
	v_cmp_lt_i32_e32 vcc, 37, v79
	s_nop 1
	v_cndmask_b32_e32 v56, v210, v56, vcc
	v_cmp_lt_i32_e32 vcc, 6, v79
	s_nop 1
	v_cndmask_b32_e32 v41, v210, v41, vcc
	v_cmp_lt_i32_e32 vcc, 38, v79
	s_nop 1
	v_cndmask_b32_e32 v57, v210, v57, vcc
	v_cmp_lt_i32_e32 vcc, 15, v79
	s_nop 1
	v_cndmask_b32_e32 v42, v210, v42, vcc
	v_cmp_lt_i32_e32 vcc, 47, v79
	s_nop 1
	v_cndmask_b32_e32 v58, v210, v58, vcc
	v_cmp_lt_i32_e32 vcc, 16, v79
	s_nop 1
	v_cndmask_b32_e32 v43, v210, v43, vcc
	v_cmp_lt_i32_e32 vcc, 48, v79
	s_nop 1
	v_cndmask_b32_e32 v59, v210, v59, vcc
	v_cmp_lt_i32_e32 vcc, 17, v79
	s_nop 1
	v_cndmask_b32_e32 v44, v210, v44, vcc
	v_cmp_lt_i32_e32 vcc, 49, v79
	s_nop 1
	v_cndmask_b32_e32 v60, v210, v60, vcc
	v_cmp_lt_i32_e32 vcc, 18, v79
	s_nop 1
	v_cndmask_b32_e32 v45, v210, v45, vcc
	v_cmp_lt_i32_e32 vcc, 50, v79
	s_nop 1
	v_cndmask_b32_e32 v61, v210, v61, vcc
	v_cmp_lt_i32_e32 vcc, 19, v79
	s_nop 1
	v_cndmask_b32_e32 v46, v210, v46, vcc
	v_cmp_lt_i32_e32 vcc, 51, v79
	s_nop 1
	v_cndmask_b32_e32 v62, v210, v62, vcc
	v_cmp_lt_i32_e32 vcc, 20, v79
	s_nop 1
	v_cndmask_b32_e32 v47, v210, v47, vcc
	v_cmp_lt_i32_e32 vcc, 52, v79
	s_nop 1
	v_cndmask_b32_e32 v63, v210, v63, vcc
	v_cmp_lt_i32_e32 vcc, 21, v79
	s_nop 1
	v_cndmask_b32_e32 v48, v210, v48, vcc
	v_cmp_lt_i32_e32 vcc, 53, v79
	s_nop 1
	v_cndmask_b32_e32 v64, v210, v64, vcc
	v_cmp_lt_i32_e32 vcc, 22, v79
	s_nop 1
	v_cndmask_b32_e32 v49, v210, v49, vcc
	v_cmp_lt_i32_e32 vcc, 54, v79
	s_nop 1
	v_cndmask_b32_e32 v65, v210, v65, vcc

; template <int MODE>
; DI void bias_init(f32x16& s0, f32x16& s1, const TP& tp, float fbm, int hi) {
; #pragma unroll
;     for (int r = 0; r < 16; ++r) {
;         const int kvc = 16 * (r >> 3) + (r & 7);
;         if (MODE == 0) { s0[r] = __builtin_fmaf(-L2E, tp.cs[kvc + 8 * hi], fbm); s1[r] = __builtin_fmaf(-L2E, tp.cs[kvc + 32 + 8 * hi], fbm); }
;         else { s0[r] = __builtin_fmaf(tp.sl, (float)kvc, fbm); s1[r] = __builtin_fmaf(tp.sl, (float)(kvc + 32), fbm); }
;     }
; }
; DI float max3_asm(float a, float b, float c) { float r; asm("v_max3_f32 %0, %1, %2, %3" : "=v"(r) : "v"(a), "v"(b), "v"(c)); return r; }
; template <bool MASK>
; DI float mask_rowmax(f32x16& s0, f32x16& s1, const TP& tp) {
;     if (MASK) {
; #pragma unroll
;         for (int r = 0; r < 16; ++r) {
;             const int kvc = 16 * (r >> 3) + (r & 7);
;             const bool v0 = tp.sel && (kvc <= tp.lim) && (kvc > tp.lim2), v1 = tp.sel && (kvc + 32 <= tp.lim) && (kvc + 32 > tp.lim2);
;             s0[r] = v0 ? s0[r] : -1e30f; s1[r] = v1 ? s1[r] : -1e30f;
;         }
;     }
;     const float seed = __builtin_fminf(s0[15], s1[15]);
;     float ma = seed, mb = seed;
; #pragma unroll
;     for (int r = 0; r < 16; r += 2) { ma = max3_asm(ma, s0[r], s1[r]); mb = max3_asm(mb, s0[r + 1], s1[r + 1]); }
;     const float mx = fmaxf(ma, mb);
;     return fmaxf(mx, __shfl_xor(mx, 32));
; }
; template <int MODE, bool MASK, bool WITH_O>
; DI void attn_tile_t(lptr Kt, lptr Vt, const bf16x8 (&qf)[4], f32x16& o0, f32x16& o1, RowState& rs, const TP& tp, int lane) {
;     const int hi = lane >> 5;
;     f32x16 s0, s1;
;     bias_init<MODE>(s0, s1, tp, tp.fb - rs.mref, hi);
;     qk_acc(Kt, qf, s0, s1, lane);
;     const float mx = mask_rowmax<MASK>(s0, s1, tp);
;     const bool was = rs.seen; rs.seen = was || (mx > -1e29f);
;     const bool trig = (mx > 8.f) || (!was && mx > -1e29f && mx < -8.f);
;     if (__builtin_expect(__any(trig), 0)) {
; DI void cmpwin_unit(const Params& P, lptr L, int u, int tid, int lane, int wid) {
;     ...
;             const int kv0 = (jw0 + jt) * 64;
;             TP tp; tp.cs = nullptr; tp.sl = sl; tp.fb = sl * (float)(kv0 + 8 * hi - t); tp.lim = t - kv0 - 8 * hi; tp.lim2 = tp.lim - 512; tp.sel = true;
;             const bool full = (kv0 + 63 <= tq0) && (tq0 + 31 - kv0 < 512);
;             attn_tile<1>(Kt, Vt, qf, o0, o1, rs, tp, !full, lane);
.LBB0_581:
	s_and_b32 s54, s53, 1
	s_mul_i32 s2, s54, 0x2400
	v_add_u32_e32 v34, s43, v161
	s_add_i32 s55, s2, 0
	s_add_i32 s2, s43, 63
	v_cvt_f32_i32_e32 v34, v34
	s_cmp_gt_u32 s2, s81
	s_cselect_b64 s[2:3], -1, 0
	s_cmp_lt_i32 s43, s23
	s_cselect_b64 s[28:29], -1, 0
	s_or_b64 s[2:3], s[2:3], s[28:29]
	v_mul_f32_e32 v216, v150, v34
	s_andn2_b64 vcc, exec, s[2:3]
	s_mov_b64 s[2:3], -1
	s_cbranch_vccz .LBB0_590
	v_add3_u32 v234, s55, v131, v133
	ds_read_b128 v[34:37], v234 offset:4608
	ds_read_b128 v[38:41], v234
	ds_read_b128 v[42:45], v234 offset:32
	ds_read_b128 v[46:49], v234 offset:4640
	ds_read_b128 v[50:53], v234 offset:64
	ds_read_b128 v[54:57], v234 offset:4672
	ds_read_b128 v[58:61], v234 offset:96
	ds_read_b128 v[62:65], v234 offset:4704
	s_mov_b32 s2, 2.0
	v_sub_f32_e32 v232, v216, v215
	s_mov_b32 s3, 0x40400000
	v_pk_fma_f32 v[84:85], v[166:167], s[2:3], v[232:233] op_sel_hi:[1,1,0]
	s_mov_b32 s2, 4.0
	s_mov_b32 s3, 0x40a00000
	v_pk_fma_f32 v[86:87], v[166:167], s[2:3], v[232:233] op_sel_hi:[1,1,0]
	s_mov_b32 s2, 0x40c00000
	s_mov_b32 s3, 0x40e00000
	v_pk_fma_f32 v[88:89], v[166:167], s[2:3], v[232:233] op_sel_hi:[1,1,0]
	s_mov_b32 s2, 0x41800000
	s_mov_b32 s3, 0x41880000
	v_pk_fma_f32 v[90:91], v[166:167], s[2:3], v[232:233] op_sel_hi:[1,1,0]
	s_mov_b32 s2, 0x41900000
	s_mov_b32 s3, 0x41980000
	v_pk_fma_f32 v[92:93], v[166:167], s[2:3], v[232:233] op_sel_hi:[1,1,0]
	s_mov_b32 s2, 0x41a00000
	s_mov_b32 s3, 0x41a80000
	v_mov_b32_e32 v151, v150
	v_fma_f32 v82, 0, v150, v232
	v_add_f32_e32 v83, v150, v232
	v_pk_fma_f32 v[94:95], v[166:167], s[2:3], v[232:233] op_sel_hi:[1,1,0]
	v_pk_fma_f32 v[96:97], v[166:167], s[18:19], v[232:233] op_sel_hi:[1,1,0]
	v_pk_fma_f32 v[80:81], v[150:151], s[4:5], v[232:233] op_sel_hi:[1,1,0]
	v_pk_fma_f32 v[78:79], v[150:151], s[14:15], v[232:233] op_sel_hi:[1,1,0]
	v_pk_fma_f32 v[76:77], v[150:151], s[16:17], v[232:233] op_sel_hi:[1,1,0]
	v_pk_fma_f32 v[74:75], v[150:151], s[94:95], v[232:233] op_sel_hi:[1,1,0]
	v_pk_fma_f32 v[72:73], v[150:151], s[96:97], v[232:233] op_sel_hi:[1,1,0]
	v_pk_fma_f32 v[70:71], v[150:151], s[84:85], v[232:233] op_sel_hi:[1,1,0]
	v_pk_fma_f32 v[68:69], v[150:151], s[72:73], v[232:233] op_sel_hi:[1,1,0]
	v_pk_fma_f32 v[66:67], v[168:169], s[44:45], v[232:233] op_sel_hi:[1,1,0]
	s_setprio 1
	s_waitcnt lgkmcnt(6)
	v_mfma_f32_32x32x16_bf16 v[82:97], v[38:41], v[98:101], v[82:97]
	v_mfma_f32_32x32x16_bf16 v[66:81], v[34:37], v[98:101], v[66:81]
	s_waitcnt lgkmcnt(5)
	v_mfma_f32_32x32x16_bf16 v[82:97], v[42:45], v[102:105], v[82:97]
	s_waitcnt lgkmcnt(4)
	v_mfma_f32_32x32x16_bf16 v[66:81], v[46:49], v[102:105], v[66:81]
	s_waitcnt lgkmcnt(3)
	v_mfma_f32_32x32x16_bf16 v[82:97], v[50:53], v[106:109], v[82:97]
	s_waitcnt lgkmcnt(2)
	v_mfma_f32_32x32x16_bf16 v[66:81], v[54:57], v[106:109], v[66:81]
	s_waitcnt lgkmcnt(1)
	v_mfma_f32_32x32x16_bf16 v[82:97], v[58:61], v[110:113], v[82:97]
	s_waitcnt lgkmcnt(0)
	v_mfma_f32_32x32x16_bf16 v[66:81], v[62:65], v[110:113], v[66:81]
	s_setprio 0
	s_nop 10
	v_max_f32_e32 v34, v81, v81
	v_max_f32_e32 v35, v97, v97
	v_min_f32_e32 v34, v35, v34
	v_max3_f32 v35, v34, v82, v66
	v_max3_f32 v34, v34, v83, v67
	s_mov_b32 s2, 0xefa18f08
	v_max3_f32 v35, v35, v84, v68
	v_max3_f32 v34, v34, v85, v69
	s_mov_b64 s[30:31], -1
	v_max3_f32 v35, v35, v86, v70
	v_max3_f32 v34, v34, v87, v71
	s_nop 0
	v_max3_f32 v35, v35, v88, v72
	v_max3_f32 v34, v34, v89, v73
	s_nop 0
	v_max3_f32 v35, v35, v90, v74
	v_max3_f32 v34, v34, v91, v75
	s_nop 0
	v_max3_f32 v35, v35, v92, v76
	v_max3_f32 v34, v34, v93, v77
	s_nop 0
	v_max3_f32 v35, v35, v94, v78
	v_max3_f32 v34, v34, v95, v79
	s_nop 0
	v_max3_f32 v35, v35, v96, v80
	v_max3_f32 v34, v34, v97, v81
	s_nop 0
	v_max_f32_e32 v34, v34, v34
	v_max_f32_e32 v35, v35, v35
	v_max_f32_e32 v34, v35, v34
	v_mov_b32_e32 v35, v34
	s_nop 1
	v_permlane32_swap_b32_e32 v35, v34
	s_waitcnt lgkmcnt(0)
	v_max_f32_e32 v218, v34, v35
	v_cmp_lt_f32_e64 s[28:29], s2, v218
	s_mov_b32 s2, 0x41000000
	v_cmp_lt_f32_e32 vcc, s2, v218
	s_mov_b32 s30, 0xc1000000
	v_cmp_gt_f32_e64 s[30:31], s30, v218
	s_and_b64 s[30:31], s[30:31], s[28:29]
	s_andn2_b64 s[30:31], s[30:31], s[24:25]
	s_or_b64 s[30:31], s[30:31], vcc
	s_and_b64 vcc, exec, s[30:31]
	v_mov_b32_e32 v217, v163
	v_mov_b32_e32 v151, v215
	s_cbranch_vccnz .LBB0_595

; template <int MODE>
; DI void bias_init(f32x16& s0, f32x16& s1, const TP& tp, float fbm, int hi) {
; #pragma unroll
;     for (int r = 0; r < 16; ++r) {
;         const int kvc = 16 * (r >> 3) + (r & 7);
;         if (MODE == 0) { s0[r] = __builtin_fmaf(-L2E, tp.cs[kvc + 8 * hi], fbm); s1[r] = __builtin_fmaf(-L2E, tp.cs[kvc + 32 + 8 * hi], fbm); }
;         else { s0[r] = __builtin_fmaf(tp.sl, (float)kvc, fbm); s1[r] = __builtin_fmaf(tp.sl, (float)(kvc + 32), fbm); }
;     }
; }
; DI float max3_asm(float a, float b, float c) { float r; asm("v_max3_f32 %0, %1, %2, %3" : "=v"(r) : "v"(a), "v"(b), "v"(c)); return r; }
; template <bool MASK>
; DI float mask_rowmax(f32x16& s0, f32x16& s1, const TP& tp) {
;     if (MASK) {
; #pragma unroll
;         for (int r = 0; r < 16; ++r) {
;             const int kvc = 16 * (r >> 3) + (r & 7);
;             const bool v0 = tp.sel && (kvc <= tp.lim) && (kvc > tp.lim2), v1 = tp.sel && (kvc + 32 <= tp.lim) && (kvc + 32 > tp.lim2);
;             s0[r] = v0 ? s0[r] : -1e30f; s1[r] = v1 ? s1[r] : -1e30f;
;         }
;     }
;     const float seed = __builtin_fminf(s0[15], s1[15]);
;     float ma = seed, mb = seed;
; #pragma unroll
;     for (int r = 0; r < 16; r += 2) { ma = max3_asm(ma, s0[r], s1[r]); mb = max3_asm(mb, s0[r + 1], s1[r + 1]); }
;     const float mx = fmaxf(ma, mb);
;     return fmaxf(mx, __shfl_xor(mx, 32));
; }
; template <int MODE, bool MASK, bool WITH_O>
; DI void attn_tile_t(lptr Kt, lptr Vt, const bf16x8 (&qf)[4], f32x16& o0, f32x16& o1, RowState& rs, const TP& tp, int lane) {
;     const int hi = lane >> 5;
;     f32x16 s0, s1;
;     bias_init<MODE>(s0, s1, tp, tp.fb - rs.mref, hi);
;     qk_acc(Kt, qf, s0, s1, lane);
;     const float mx = mask_rowmax<MASK>(s0, s1, tp);
;     const bool was = rs.seen; rs.seen = was || (mx > -1e29f);
;     const bool trig = (mx > 8.f) || (!was && mx > -1e29f && mx < -8.f);
;     if (__builtin_expect(__any(trig), 0)) {
; DI void slc_unit(const Params& P, lptr L, int u, int tid, int lane, int wid) {
;     ...
;         const int j = (int)list[jt], kv0 = j * 64;
;         const bool sel = (sm[ql * 8 + (j >> 5)] >> (j & 31)) & 1u;
;         if (__any(sel)) {
;             TP tp; tp.cs = nullptr; tp.sl = sl; tp.fb = sl * (float)(kv0 + 8 * hi - t); tp.lim = t - kv0 - 8 * hi; tp.lim2 = -(1 << 30); tp.sel = sel;
;             attn_tile<1>(Kt, Vt, qf, o0, o1, rs, tp, true, lane);
.LBB0_613:
	v_mov_b32_e32 v0, v253
	s_and_b32 s31, s0, 1
	v_and_b32_e32 v35, 31, v253
	s_waitcnt lgkmcnt(0)
	v_lshrrev_b32_e32 v36, v0, v255
	v_bfe_u32 v34, v255, v35, 1
	v_and_b32_e32 v35, 1, v36
	v_mov_b32_e32 v253, v254
	v_cmp_ne_u32_e32 vcc, 0, v34
	v_cmp_eq_u32_e64 s[28:29], 1, v35
	s_cbranch_vccz .LBB0_618
	s_mul_i32 s33, s31, 0x2400
	v_add_u32_e32 v232, s33, v170
	ds_read_b128 v[102:105], v232 offset:4608
	ds_read_b128 v[106:109], v232
	ds_read_b128 v[110:113], v232 offset:32
	ds_read_b128 v[114:117], v232 offset:4640
	ds_read_b128 v[118:121], v232 offset:64
	ds_read_b128 v[158:161], v232 offset:4672
	ds_read_b128 v[162:165], v232 offset:96
	ds_read_b128 v[166:169], v232 offset:4704
	v_lshl_or_b32 v0, v0, 6, v126
	v_sub_u32_e32 v34, v0, v91
	v_cvt_f32_i32_e32 v34, v34
	s_mov_b32 s0, 2.0
	v_sub_u32_e32 v152, v91, v0
	s_mov_b32 s1, 0x40400000
	v_cmp_lt_i32_e32 vcc, 54, v152
	v_fma_f32 v0, v150, v34, -v101
	s_cmp_eq_u64 vcc, exec
	s_cselect_b64 s[98:99], -1, 0
	s_orn2_b64 s[100:101], s[28:29], s[98:99]
	v_cndmask_b32_e64 v0, v210, v0, s[100:101]
	v_pk_fma_f32 v[36:37], v[94:95], s[0:1], v[0:1] op_sel_hi:[1,1,0]
	s_mov_b32 s0, 4.0
	s_mov_b32 s1, 0x40a00000
	v_pk_fma_f32 v[38:39], v[94:95], s[0:1], v[0:1] op_sel_hi:[1,1,0]
	s_mov_b32 s0, 0x40c00000
	s_mov_b32 s1, 0x40e00000
	v_pk_fma_f32 v[40:41], v[94:95], s[0:1], v[0:1] op_sel_hi:[1,1,0]
	s_mov_b32 s0, 0x41800000
	s_mov_b32 s1, 0x41880000
	v_pk_fma_f32 v[42:43], v[94:95], s[0:1], v[0:1] op_sel_hi:[1,1,0]
	s_mov_b32 s0, 0x41900000
	s_mov_b32 s1, 0x41980000
	v_pk_fma_f32 v[44:45], v[94:95], s[0:1], v[0:1] op_sel_hi:[1,1,0]
	s_mov_b32 s0, 0x41a00000
	s_mov_b32 s1, 0x41a80000
	v_mov_b32_e32 v151, v150
	v_fma_f32 v34, 0, v150, v0
	v_add_f32_e32 v35, v150, v0
	v_pk_fma_f32 v[46:47], v[94:95], s[0:1], v[0:1] op_sel_hi:[1,1,0]
	v_pk_fma_f32 v[48:49], v[94:95], s[18:19], v[0:1] op_sel_hi:[1,1,0]
	v_pk_fma_f32 v[64:65], v[150:151], s[4:5], v[0:1] op_sel_hi:[1,1,0]
	v_pk_fma_f32 v[62:63], v[150:151], s[14:15], v[0:1] op_sel_hi:[1,1,0]
	v_pk_fma_f32 v[60:61], v[150:151], s[16:17], v[0:1] op_sel_hi:[1,1,0]
	v_pk_fma_f32 v[58:59], v[150:151], s[94:95], v[0:1] op_sel_hi:[1,1,0]
	v_pk_fma_f32 v[56:57], v[150:151], s[96:97], v[0:1] op_sel_hi:[1,1,0]
	v_pk_fma_f32 v[54:55], v[150:151], s[84:85], v[0:1] op_sel_hi:[1,1,0]
	v_pk_fma_f32 v[52:53], v[150:151], s[72:73], v[0:1] op_sel_hi:[1,1,0]
	v_pk_fma_f32 v[50:51], v[96:97], s[44:45], v[0:1] op_sel_hi:[1,1,0]
	s_setprio 1
	s_waitcnt lgkmcnt(6)
	v_mfma_f32_32x32x16_bf16 v[34:49], v[106:109], v[66:69], v[34:49]
	v_mfma_f32_32x32x16_bf16 v[50:65], v[102:105], v[66:69], v[50:65]
	s_waitcnt lgkmcnt(5)
	v_mfma_f32_32x32x16_bf16 v[34:49], v[110:113], v[70:73], v[34:49]
	s_waitcnt lgkmcnt(4)
	v_mfma_f32_32x32x16_bf16 v[50:65], v[114:117], v[70:73], v[50:65]
	s_waitcnt lgkmcnt(3)
	v_mfma_f32_32x32x16_bf16 v[34:49], v[118:121], v[74:77], v[34:49]
	s_waitcnt lgkmcnt(2)
	v_mfma_f32_32x32x16_bf16 v[50:65], v[158:161], v[74:77], v[50:65]
	s_waitcnt lgkmcnt(1)
	v_mfma_f32_32x32x16_bf16 v[34:49], v[162:165], v[78:81], v[34:49]
	s_waitcnt lgkmcnt(0)
	v_mfma_f32_32x32x16_bf16 v[50:65], v[166:169], v[78:81], v[50:65]
	s_setprio 0
	s_and_b64 vcc, exec, s[98:99]
	s_cbranch_vccz .Lslc_masked
	s_nop 10
	v_max_f32_e32 v252, v65, v65
	v_max_f32_e32 v228, v49, v49
	v_min_f32_e32 v252, v228, v252
	v_max3_f32 v228, v252, v34, v50
	v_max3_f32 v252, v252, v35, v51
	s_mov_b32 s0, 0xefa18f08
	v_max3_f32 v228, v228, v36, v52
	v_max3_f32 v252, v252, v37, v53
	s_nop 0
	v_max3_f32 v228, v228, v38, v54
	v_max3_f32 v252, v252, v39, v55
	s_nop 0
	v_max3_f32 v228, v228, v40, v56
	v_max3_f32 v252, v252, v41, v57
	s_nop 0
	v_max3_f32 v228, v228, v42, v58
	v_max3_f32 v252, v252, v43, v59
	s_nop 0
	v_max3_f32 v228, v228, v44, v60
	v_max3_f32 v252, v252, v45, v61
	s_nop 0
	v_max3_f32 v228, v228, v46, v62
	v_max3_f32 v252, v252, v47, v63
	s_nop 0
	v_max3_f32 v228, v228, v48, v64
	v_max3_f32 v252, v252, v49, v65
	s_nop 0
	v_max_f32_e32 v252, v252, v252
	v_max_f32_e32 v228, v228, v228
	v_max_f32_e32 v252, v228, v252
	v_mov_b32_e32 v228, v252
	s_nop 1
	v_permlane32_swap_b32_e32 v228, v252
	s_waitcnt lgkmcnt(0)
	v_max_f32_e32 v252, v252, v228
	v_cmp_lt_f32_e64 s[28:29], s0, v252
	s_mov_b32 s0, 0x41000000
	v_cmp_lt_f32_e32 vcc, s0, v252
	s_mov_b32 s0, 0xc1000000
	v_cmp_gt_f32_e64 s[0:1], s0, v252
	s_and_b64 s[0:1], s[0:1], s[28:29]
	s_andn2_b64 s[0:1], s[0:1], s[22:23]
	s_or_b64 s[0:1], s[0:1], vcc
	s_and_b64 vcc, exec, s[0:1]
	s_cbranch_vccnz .Lsf_rare
; template <int MODE, bool MASK, bool WITH_O>
; DI void attn_tile_t(lptr Kt, lptr Vt, const bf16x8 (&qf)[4], f32x16& o0, f32x16& o1, RowState& rs, const TP& tp, int lane) {
;     ...
;     } else {
;         const int i = lane & 31;
;         lptr vp = Vt + i * KPB + hi * 16;
;         float sum = 0.f;
;     ...
;         PV_STEP(s0, 0, 0) PV_STEP(s0, 8, 32) PV_STEP(s1, 0, 64) PV_STEP(s1, 8, 96)
;     ...
;         rs.l += sum;
	v_exp_f32_e32 v252, v34
	v_exp_f32_e32 v103, v35
	v_exp_f32_e32 v111, v36
	v_exp_f32_e32 v105, v37
	v_add_f32_e32 v106, 0, v252
	v_add_f32_e32 v106, v103, v106
	v_add_f32_e32 v104, v111, v106
	v_exp_f32_e32 v106, v38
	v_exp_f32_e32 v107, v39
	v_add_u32_e32 v228, s33, v172
	v_exp_f32_e32 v108, v40
	ds_read_b128 v[236:239], v228 offset:18432
	ds_read_b128 v[240:243], v228 offset:23040
	v_add_f32_e32 v104, v105, v104
	v_exp_f32_e32 v109, v41
	v_add_f32_e32 v104, v106, v104
	v_add_f32_e32 v104, v107, v104
	v_add_f32_e32 v104, v108, v104
	v_add_f32_e32 v110, v109, v104
	v_cvt_pk_bf16_f32 v104, v252, v103
	v_cvt_pk_bf16_f32 v105, v111, v105
	v_cvt_pk_bf16_f32 v106, v106, v107
	v_cvt_pk_bf16_f32 v107, v108, v109
	s_or_b64 s[22:23], s[22:23], s[28:29]
	s_waitcnt lgkmcnt(1)
	v_mfma_f32_32x32x16_bf16 v[18:33], v[236:239], v[104:107], v[18:33]
	s_waitcnt lgkmcnt(0)
	v_mfma_f32_32x32x16_bf16 v[2:17], v[240:243], v[104:107], v[2:17]
	v_exp_f32_e32 v252, v42
	v_exp_f32_e32 v43, v43
	v_exp_f32_e32 v103, v44
	v_exp_f32_e32 v44, v45
	v_add_f32_e32 v229, v252, v110
	v_exp_f32_e32 v45, v46
	v_add_f32_e32 v229, v43, v229
	v_exp_f32_e32 v46, v47
	v_add_f32_e32 v42, v103, v229
	v_exp_f32_e32 v47, v48
	ds_read_b128 v[236:239], v228 offset:18464
	ds_read_b128 v[240:243], v228 offset:23072
	v_add_f32_e32 v42, v44, v42
	v_exp_f32_e32 v48, v49
	v_add_f32_e32 v42, v45, v42
	v_add_f32_e32 v42, v46, v42
	v_add_f32_e32 v42, v47, v42
	v_add_f32_e32 v229, v48, v42
	v_cvt_pk_bf16_f32 v42, v252, v43
	v_cvt_pk_bf16_f32 v43, v103, v44
	v_cvt_pk_bf16_f32 v44, v45, v46
	v_cvt_pk_bf16_f32 v45, v47, v48
	s_waitcnt lgkmcnt(1)
	s_nop 0
	v_mfma_f32_32x32x16_bf16 v[18:33], v[236:239], v[42:45], v[18:33]
	s_waitcnt lgkmcnt(0)
	v_mfma_f32_32x32x16_bf16 v[2:17], v[240:243], v[42:45], v[2:17]
	v_exp_f32_e32 v230, v50
	v_exp_f32_e32 v51, v51
	v_exp_f32_e32 v231, v52
	v_exp_f32_e32 v52, v53
	v_add_f32_e32 v229, v230, v229
	v_exp_f32_e32 v53, v54
	v_add_f32_e32 v229, v51, v229
	v_exp_f32_e32 v54, v55
	v_add_f32_e32 v50, v231, v229
	v_exp_f32_e32 v55, v56
	ds_read_b128 v[42:45], v228 offset:18496
	ds_read_b128 v[46:49], v228 offset:23104
	v_add_f32_e32 v50, v52, v50
	v_exp_f32_e32 v41, v57
	v_add_f32_e32 v50, v53, v50
	v_add_f32_e32 v50, v54, v50
	v_add_f32_e32 v50, v55, v50
	v_add_f32_e32 v56, v41, v50
	v_cvt_pk_bf16_f32 v50, v230, v51
	v_cvt_pk_bf16_f32 v51, v231, v52
	v_cvt_pk_bf16_f32 v52, v53, v54
	v_cvt_pk_bf16_f32 v53, v55, v41
	s_waitcnt lgkmcnt(1)
	s_nop 0
	v_mfma_f32_32x32x16_bf16 v[18:33], v[42:45], v[50:53], v[18:33]
	s_waitcnt lgkmcnt(0)
	v_mfma_f32_32x32x16_bf16 v[2:17], v[46:49], v[50:53], v[2:17]
	v_exp_f32_e32 v38, v58
	v_exp_f32_e32 v34, v59
	v_exp_f32_e32 v0, v60
	v_exp_f32_e32 v35, v61
	v_add_f32_e32 v41, v38, v56
	v_exp_f32_e32 v36, v62
	ds_read_b128 v[42:45], v228 offset:18528
	ds_read_b128 v[46:49], v228 offset:23136
	v_add_f32_e32 v41, v34, v41
	v_exp_f32_e32 v37, v63
	v_exp_f32_e32 v39, v64
	v_exp_f32_e32 v40, v65
	v_add_f32_e32 v41, v0, v41
	v_add_f32_e32 v41, v35, v41
	v_add_f32_e32 v41, v36, v41
	v_add_f32_e32 v41, v37, v41
	v_cvt_pk_bf16_f32 v34, v38, v34
	v_cvt_pk_bf16_f32 v35, v0, v35
	v_cvt_pk_bf16_f32 v36, v36, v37
	v_cvt_pk_bf16_f32 v37, v39, v40
	v_add_f32_e32 v41, v39, v41
	v_add_f32_e32 v41, v40, v41
	s_waitcnt lgkmcnt(1)
	v_mfma_f32_32x32x16_bf16 v[18:33], v[42:45], v[34:37], v[18:33]
	s_waitcnt lgkmcnt(0)
	v_mfma_f32_32x32x16_bf16 v[2:17], v[46:49], v[34:37], v[2:17]
	v_add_f32_e32 v100, v100, v41
	s_branch .LBB0_618
